# EpiResid first-unit init: wait only for the 16 residual loads (vmcnt(8)) instead of draining the 8 prologue tile DMAs
# speedup vs baseline: 1.0026x; 1.0026x over previous
; DI float bflo(unsigned u) { return __uint_as_float(u << 16); }
; DI float bfhi(unsigned u) { return __uint_as_float(u & 0xffff0000u); }
;   DI void init(f32x4 (&acc)[2][2][4][2], const Unit&, int, int, int, int) const { acc_zero(acc); }
;   DI void init(f32x4 (&acc)[2][2][4][2], const Unit&, int, int, int, int) const { acc_zero(acc); }
; #define PG8_STAGE(bufoff, gbase, voff) do { _Pragma("unroll") for (int _i = 0; _i < 2; ++_i) \
;     __builtin_amdgcn_global_load_lds((const unsigned*)((const char*)(gbase) + (voff)[_i]), (PG8_LAS unsigned*)(lds + (bufoff) + ldsw + _i * 8192), 16, 0, 0); } while (0)
; #define PG8_WAIT_V(n) asm volatile("s_waitcnt vmcnt(" #n ")" ::: "memory")
; #define PG8_BAR __builtin_amdgcn_s_barrier()
;   DI void init(f32x4 (&acc)[2][2][4][2], const Unit& u, int wr, int wc, int fr, int fq) const {
;     const int row0 = u.pm * BM + wr * 64 + fr, col0 = u.pn * BM + wc * 32 + 8 * fq; const float ic = 1.f / coef;
; #pragma unroll
;     for (int ai = 0; ai < 2; ++ai)
; #pragma unroll
;       for (int m = 0; m < 4; ++m) { const bf16_t* rowp = src + (size_t)(row0 + ai * HALF + m * 16) * DM + col0;
; #pragma unroll
;         for (int bj = 0; bj < 2; ++bj) { const u32x4 w = *(const u32x4*)(rowp + bj * HALF);
;           acc[ai][bj][m][0] = (f32x4){bflo(w.x), bfhi(w.x), bflo(w.y), bfhi(w.y)} * ic; acc[ai][bj][m][1] = (f32x4){bflo(w.z), bfhi(w.z), bflo(w.w), bfhi(w.w)} * ic; } }
; template <class Epi>
; DI void gemm_phase(const bf16_t* __restrict__ gA, const bf16_t* __restrict__ gBt, int M, int N, int K, const Epi& E, char* lds_generic) {
;     ...
;   PG8_STAGE(PG8_SB(0, 0), cB, voffB); PG8_STAGE(PG8_SA(0, 0), cA, voffA); PG8_STAGE(PG8_SB(0, 1), cB + hstep, voffB); PG8_STAGE(PG8_SA(0, 1), cA + hstep, voffA);
;   if (wr == 1) PG8_BAR;
;   PG8_WAIT_V(4); PG8_BAR;
;   PG8_STAGE(PG8_SB(1, 0), cB + kstep, voffB); PG8_STAGE(PG8_SA(1, 0), cA + kstep, voffA); PG8_STAGE(PG8_SB(1, 1), cB + hstep + kstep, voffB);
;   PG8_WAIT_V(6); PG8_BAR;
.LBB0_502:
	v_readlane_b32 s22, v254, 45
	v_readlane_b32 s23, v254, 46
	s_waitcnt vmcnt(8)
	v_lshlrev_b32_e32 v102, 16, v42
	v_and_b32_e32 v103, 0xffff0000, v42
	v_lshlrev_b32_e32 v104, 16, v43
	v_and_b32_e32 v105, 0xffff0000, v43
	v_lshlrev_b32_e32 v114, 16, v44
	v_and_b32_e32 v115, 0xffff0000, v44
	v_lshlrev_b32_e32 v116, 16, v45
	v_and_b32_e32 v117, 0xffff0000, v45
	v_lshlrev_b32_e32 v86, 16, v22
	v_and_b32_e32 v87, 0xffff0000, v22
	v_lshlrev_b32_e32 v88, 16, v23
	v_and_b32_e32 v89, 0xffff0000, v23
	v_lshlrev_b32_e32 v98, 16, v24
	v_and_b32_e32 v99, 0xffff0000, v24
	v_lshlrev_b32_e32 v100, 16, v25
	v_and_b32_e32 v101, 0xffff0000, v25
	v_lshlrev_b32_e32 v42, 16, v38
	v_and_b32_e32 v43, 0xffff0000, v38
	v_lshlrev_b32_e32 v44, 16, v39
	v_and_b32_e32 v45, 0xffff0000, v39
	v_lshlrev_b32_e32 v22, 16, v40
	v_and_b32_e32 v23, 0xffff0000, v40
	v_lshlrev_b32_e32 v24, 16, v41
	v_and_b32_e32 v25, 0xffff0000, v41
	v_lshlrev_b32_e32 v38, 16, v46
	v_and_b32_e32 v39, 0xffff0000, v46
	v_lshlrev_b32_e32 v40, 16, v47
	v_and_b32_e32 v41, 0xffff0000, v47
	v_lshl_add_u64 v[46:47], s[22:23], 0, v[0:1]
	v_mov_b32_e32 v131, v1
	v_readlane_b32 s28, v254, 41
	s_add_i32 s8, s6, 0x18000
	v_lshlrev_b32_e32 v90, 16, v58
	v_and_b32_e32 v91, 0xffff0000, v58
	v_lshlrev_b32_e32 v92, 16, v59
	v_and_b32_e32 v93, 0xffff0000, v59
	v_lshlrev_b32_e32 v82, 16, v60
	v_and_b32_e32 v83, 0xffff0000, v60
	v_lshlrev_b32_e32 v84, 16, v61
	v_and_b32_e32 v85, 0xffff0000, v61
	v_lshlrev_b32_e32 v58, 16, v18
	v_and_b32_e32 v59, 0xffff0000, v18
	v_lshlrev_b32_e32 v60, 16, v19
	v_and_b32_e32 v61, 0xffff0000, v19
	v_lshlrev_b32_e32 v74, 16, v20
	v_and_b32_e32 v75, 0xffff0000, v20
	v_lshlrev_b32_e32 v76, 16, v21
	v_and_b32_e32 v77, 0xffff0000, v21
	v_lshlrev_b32_e32 v18, 16, v48
	v_and_b32_e32 v19, 0xffff0000, v48
	v_lshlrev_b32_e32 v20, 16, v49
	v_and_b32_e32 v21, 0xffff0000, v49
	v_lshl_add_u64 v[48:49], s[22:23], 0, v[130:131]
	v_mov_b32_e32 v135, v1
	v_readlane_b32 s29, v254, 42
	v_lshl_add_u64 v[46:47], v[46:47], 0, s[10:11]
	s_mov_b32 m0, s8
	s_add_i32 s9, s6, 0x1a000
	v_lshl_add_u64 v[70:71], s[28:29], 0, v[134:135]
	v_mov_b32_e32 v133, v1
	global_load_lds_dwordx4 v[46:47], off
	v_lshl_add_u64 v[46:47], v[48:49], 0, s[10:11]
	s_mov_b32 m0, s9
	s_add_i32 s19, s6, 0x8000
	v_lshl_add_u64 v[72:73], s[28:29], 0, v[132:133]
	global_load_lds_dwordx4 v[46:47], off
	v_lshl_add_u64 v[46:47], v[70:71], 0, s[10:11]
	s_mov_b32 m0, s19
	s_add_i32 s33, s6, 0xa000
	v_readlane_b32 s24, v254, 47
	global_load_lds_dwordx4 v[46:47], off
	v_lshl_add_u64 v[46:47], v[72:73], 0, s[10:11]
	s_mov_b32 m0, s33
	s_add_i32 s35, s6, 0x1c000
	v_readlane_b32 s25, v254, 48
	global_load_lds_dwordx4 v[46:47], off
	s_nop 0
	v_lshl_add_u64 v[46:47], s[24:25], 0, v[0:1]
	s_mov_b32 m0, s35
	s_add_i32 s42, s6, 0x1e000
	global_load_lds_dwordx4 v[46:47], off
	v_lshl_add_u64 v[46:47], s[24:25], 0, v[130:131]
	s_mov_b32 m0, s42
	v_or_b32_e32 v144, s20, v140
	global_load_lds_dwordx4 v[46:47], off
	s_waitcnt vmcnt(10)
	s_barrier
	v_lshlrev_b32_e32 v145, 6, v144
	v_lshlrev_b32_e32 v146, 4, v136
	s_movk_i32 s20, 0x3c0
	v_lshlrev_b32_e32 v147, 2, v144
	v_and_or_b32 v145, v145, s20, v146
	s_lshl_b32 s1, s1, 13
	v_and_b32_e32 v147, 32, v147
	v_lshl_or_b32 v146, v140, 6, v146
	v_lshlrev_b32_e32 v140, 2, v140
	v_bitop3_b32 v145, v145, s1, v147 bitop3:0xde
	s_lshl_b32 s1, s5, 12
	v_and_b32_e32 v140, 32, v140
	v_bitop3_b32 v146, v146, s1, v140 bitop3:0xde
	v_add_u32_e32 v146, 0x10000, v146
	v_cmp_eq_u32_e64 s[36:37], 0, v136
	v_lshlrev_b32_e32 v136, 14, v143
	v_lshlrev_b32_e32 v140, 14, v138
	v_and_b32_e32 v136, 0xffff8000, v136
	v_and_b32_e32 v140, 0xffff8000, v140
	s_waitcnt vmcnt(6)
	v_or_b32_e32 v147, s0, v137
	v_lshl_add_u32 v136, v142, 11, v136
	v_and_b32_e32 v137, 1, v143
	v_lshl_add_u32 v139, v139, 11, v140
	v_and_b32_e32 v138, 1, v138
	v_readlane_b32 s0, v254, 35
	v_lshl_or_b32 v136, v137, 6, v136
	v_lshl_or_b32 v138, v138, 6, v139
	v_readlane_b32 s1, v254, 36
	v_lshlrev_b32_e32 v118, 16, v62
	v_and_b32_e32 v119, 0xffff0000, v62
	v_lshlrev_b32_e32 v120, 16, v63
	v_and_b32_e32 v121, 0xffff0000, v63
	v_lshlrev_b32_e32 v110, 16, v64
	v_and_b32_e32 v111, 0xffff0000, v64
	v_lshlrev_b32_e32 v112, 16, v65
	v_and_b32_e32 v113, 0xffff0000, v65
	v_lshlrev_b32_e32 v122, 16, v54
	v_and_b32_e32 v123, 0xffff0000, v54
	v_lshlrev_b32_e32 v124, 16, v55
	v_and_b32_e32 v125, 0xffff0000, v55
	v_lshlrev_b32_e32 v126, 16, v56
	v_and_b32_e32 v127, 0xffff0000, v56
	v_lshlrev_b32_e32 v128, 16, v57
	v_and_b32_e32 v129, 0xffff0000, v57
	v_lshlrev_b32_e32 v62, 16, v50
	v_and_b32_e32 v63, 0xffff0000, v50
	v_lshlrev_b32_e32 v64, 16, v51
	v_and_b32_e32 v65, 0xffff0000, v51
	v_lshlrev_b32_e32 v50, 16, v52
	v_and_b32_e32 v51, 0xffff0000, v52
	v_lshlrev_b32_e32 v52, 16, v53
	v_and_b32_e32 v53, 0xffff0000, v53
	v_lshlrev_b32_e32 v54, 16, v10
	v_and_b32_e32 v55, 0xffff0000, v10
	v_lshlrev_b32_e32 v56, 16, v11
	v_and_b32_e32 v57, 0xffff0000, v11
	v_lshlrev_b32_e32 v66, 16, v12
	v_and_b32_e32 v67, 0xffff0000, v12
	v_lshlrev_b32_e32 v68, 16, v13
	v_and_b32_e32 v69, 0xffff0000, v13
	v_lshlrev_b32_e32 v10, 16, v2
	v_and_b32_e32 v11, 0xffff0000, v2
	v_lshlrev_b32_e32 v12, 16, v3
	v_and_b32_e32 v13, 0xffff0000, v3
	v_lshlrev_b32_e32 v2, 16, v4
	v_and_b32_e32 v3, 0xffff0000, v4
	v_lshlrev_b32_e32 v4, 16, v5
	v_and_b32_e32 v5, 0xffff0000, v5
	v_lshlrev_b32_e32 v94, 16, v14
	v_and_b32_e32 v95, 0xffff0000, v14
	v_lshlrev_b32_e32 v96, 16, v15
	v_and_b32_e32 v97, 0xffff0000, v15
	v_lshlrev_b32_e32 v106, 16, v16
	v_and_b32_e32 v107, 0xffff0000, v16
	v_lshlrev_b32_e32 v108, 16, v17
	v_and_b32_e32 v109, 0xffff0000, v17
	v_lshlrev_b32_e32 v46, 16, v30
	v_and_b32_e32 v47, 0xffff0000, v30
	v_lshlrev_b32_e32 v48, 16, v31
	v_and_b32_e32 v49, 0xffff0000, v31
	v_lshlrev_b32_e32 v30, 16, v32
	v_and_b32_e32 v31, 0xffff0000, v32
	v_lshlrev_b32_e32 v32, 16, v33
	v_and_b32_e32 v33, 0xffff0000, v33
	v_lshlrev_b32_e32 v70, 16, v6
	v_and_b32_e32 v71, 0xffff0000, v6
	v_lshlrev_b32_e32 v72, 16, v7
	v_and_b32_e32 v73, 0xffff0000, v7
	v_lshlrev_b32_e32 v78, 16, v8
	v_and_b32_e32 v79, 0xffff0000, v8
	v_lshlrev_b32_e32 v80, 16, v9
	v_and_b32_e32 v81, 0xffff0000, v9
	v_lshlrev_b32_e32 v14, 16, v26
	v_and_b32_e32 v15, 0xffff0000, v26
	v_lshlrev_b32_e32 v16, 16, v27
	v_and_b32_e32 v17, 0xffff0000, v27
	v_lshlrev_b32_e32 v6, 16, v28
	v_and_b32_e32 v7, 0xffff0000, v28
	v_lshlrev_b32_e32 v8, 16, v29
	v_and_b32_e32 v9, 0xffff0000, v29
	v_lshlrev_b32_e32 v26, 16, v34
	v_and_b32_e32 v27, 0xffff0000, v34
	v_lshlrev_b32_e32 v28, 16, v35
	v_and_b32_e32 v29, 0xffff0000, v35
	v_lshlrev_b32_e32 v34, 16, v36
	v_and_b32_e32 v35, 0xffff0000, v36
	v_lshlrev_b32_e32 v36, 16, v37
	v_and_b32_e32 v37, 0xffff0000, v37
	s_mov_b32 s53, 0
	v_lshl_add_u32 v136, v148, 1, v136
	v_mov_b32_e32 v137, v1
	v_lshl_add_u32 v138, v141, 1, v138
	v_mov_b32_e32 v139, v1
	v_readlane_b32 s20, v254, 33
	s_mov_b32 s21, s0
	s_mov_b64 s[0:1], s[22:23]
	s_barrier
	s_branch .LBB0_504

; DI float bflo(unsigned u) { return __uint_as_float(u << 16); }
; DI float bfhi(unsigned u) { return __uint_as_float(u & 0xffff0000u); }
;   DI void init(f32x4 (&acc)[2][2][4][2], const Unit&, int, int, int, int) const { acc_zero(acc); }
;   DI void init(f32x4 (&acc)[2][2][4][2], const Unit&, int, int, int, int) const { acc_zero(acc); }
; #define PG8_STAGE(bufoff, gbase, voff) do { _Pragma("unroll") for (int _i = 0; _i < 2; ++_i) \
;     __builtin_amdgcn_global_load_lds((const unsigned*)((const char*)(gbase) + (voff)[_i]), (PG8_LAS unsigned*)(lds + (bufoff) + ldsw + _i * 8192), 16, 0, 0); } while (0)
; #define PG8_WAIT_V(n) asm volatile("s_waitcnt vmcnt(" #n ")" ::: "memory")
; #define PG8_BAR __builtin_amdgcn_s_barrier()
;   DI void init(f32x4 (&acc)[2][2][4][2], const Unit& u, int wr, int wc, int fr, int fq) const {
;     const int row0 = u.pm * BM + wr * 64 + fr, col0 = u.pn * BM + wc * 32 + 8 * fq; const float ic = 1.f / coef;
; #pragma unroll
;     for (int ai = 0; ai < 2; ++ai)
; #pragma unroll
;       for (int m = 0; m < 4; ++m) { const bf16_t* rowp = src + (size_t)(row0 + ai * HALF + m * 16) * DM + col0;
; #pragma unroll
;         for (int bj = 0; bj < 2; ++bj) { const u32x4 w = *(const u32x4*)(rowp + bj * HALF);
;           acc[ai][bj][m][0] = (f32x4){bflo(w.x), bfhi(w.x), bflo(w.y), bfhi(w.y)} * ic; acc[ai][bj][m][1] = (f32x4){bflo(w.z), bfhi(w.z), bflo(w.w), bfhi(w.w)} * ic; } }
; template <class Epi>
; DI void gemm_phase(const bf16_t* __restrict__ gA, const bf16_t* __restrict__ gBt, int M, int N, int K, const Epi& E, char* lds_generic) {
;     ...
;   PG8_STAGE(PG8_SB(0, 0), cB, voffB); PG8_STAGE(PG8_SA(0, 0), cA, voffA); PG8_STAGE(PG8_SB(0, 1), cB + hstep, voffB); PG8_STAGE(PG8_SA(0, 1), cA + hstep, voffA);
;   if (wr == 1) PG8_BAR;
;   PG8_WAIT_V(4); PG8_BAR;
;   PG8_STAGE(PG8_SB(1, 0), cB + kstep, voffB); PG8_STAGE(PG8_SA(1, 0), cA + kstep, voffA); PG8_STAGE(PG8_SB(1, 1), cB + hstep + kstep, voffB);
;   PG8_WAIT_V(6); PG8_BAR;
.LBB0_671:
	s_lshl_b64 s[20:21], s[26:27], 1
	v_readlane_b32 s19, v255, 58
	s_add_u32 s26, s19, s20
	v_readlane_b32 s19, v255, 56
	s_waitcnt vmcnt(8)
	v_lshlrev_b32_e32 v118, 16, v54
	v_and_b32_e32 v119, 0xffff0000, v54
	v_lshlrev_b32_e32 v120, 16, v55
	v_and_b32_e32 v121, 0xffff0000, v55
	v_lshlrev_b32_e32 v114, 16, v56
	v_and_b32_e32 v115, 0xffff0000, v56
	v_lshlrev_b32_e32 v116, 16, v57
	v_and_b32_e32 v117, 0xffff0000, v57
	v_lshlrev_b32_e32 v54, 16, v26
	v_and_b32_e32 v55, 0xffff0000, v26
	v_lshlrev_b32_e32 v56, 16, v27
	v_and_b32_e32 v57, 0xffff0000, v27
	v_lshl_add_u64 v[26:27], s[90:91], 0, v[0:1]
	v_mov_b32_e32 v135, v1
	s_addc_u32 s27, s19, s21
	s_add_i32 s59, s12, 0x18000
	v_lshlrev_b32_e32 v94, 16, v50
	v_and_b32_e32 v95, 0xffff0000, v50
	v_lshlrev_b32_e32 v96, 16, v51
	v_and_b32_e32 v97, 0xffff0000, v51
	v_lshlrev_b32_e32 v90, 16, v52
	v_and_b32_e32 v91, 0xffff0000, v52
	v_lshlrev_b32_e32 v92, 16, v53
	v_and_b32_e32 v93, 0xffff0000, v53
	v_lshlrev_b32_e32 v50, 16, v28
	v_and_b32_e32 v51, 0xffff0000, v28
	v_lshlrev_b32_e32 v52, 16, v29
	v_and_b32_e32 v53, 0xffff0000, v29
	v_lshl_add_u64 v[28:29], s[90:91], 0, v[134:135]
	v_mov_b32_e32 v131, v1
	v_lshl_add_u64 v[26:27], v[26:27], 0, s[10:11]
	s_mov_b32 m0, s59
	s_add_i32 s60, s12, 0x1a000
	v_lshlrev_b32_e32 v70, 16, v30
	v_and_b32_e32 v71, 0xffff0000, v30
	v_lshlrev_b32_e32 v72, 16, v31
	v_and_b32_e32 v73, 0xffff0000, v31
	v_lshl_add_u64 v[30:31], s[88:89], 0, v[130:131]
	v_mov_b32_e32 v133, v1
	s_lshl_b32 s8, s8, 13
	s_lshl_b32 s22, s7, 12
	global_load_lds_dwordx4 v[26:27], off
	v_lshl_add_u64 v[26:27], v[28:29], 0, s[10:11]
	s_mov_b32 m0, s60
	s_add_i32 s62, s12, 0x8000
	s_add_i32 s72, s12, 0xa000
	v_lshlrev_b32_e32 v66, 16, v32
	v_and_b32_e32 v67, 0xffff0000, v32
	v_lshlrev_b32_e32 v68, 16, v33
	v_and_b32_e32 v69, 0xffff0000, v33
	v_lshl_add_u64 v[32:33], s[88:89], 0, v[132:133]
	global_load_lds_dwordx4 v[26:27], off
	v_lshl_add_u64 v[26:27], v[30:31], 0, s[10:11]
	s_mov_b32 m0, s62
	s_add_u32 s20, s90, 0xb0080
	global_load_lds_dwordx4 v[26:27], off
	v_lshl_add_u64 v[26:27], v[32:33], 0, s[10:11]
	s_mov_b32 m0, s72
	s_addc_u32 s21, s91, 0
	s_add_i32 s74, s12, 0x1c000
	global_load_lds_dwordx4 v[26:27], off
	v_lshl_add_u64 v[26:27], s[20:21], 0, v[0:1]
	s_mov_b32 m0, s74
	s_add_i32 s19, s12, 0x1e000
	global_load_lds_dwordx4 v[26:27], off
	v_lshl_add_u64 v[26:27], s[20:21], 0, v[134:135]
	s_mov_b32 m0, s19
	v_or_b32_e32 v144, s1, v146
	global_load_lds_dwordx4 v[26:27], off
	s_waitcnt vmcnt(10)
	s_barrier
	v_lshlrev_b32_e32 v145, 6, v144
	v_lshlrev_b32_e32 v149, 4, v136
	s_movk_i32 s1, 0x3c0
	v_lshlrev_b32_e32 v150, 2, v144
	v_and_or_b32 v145, v145, s1, v149
	v_and_b32_e32 v150, 32, v150
	v_bitop3_b32 v145, v145, s8, v150 bitop3:0xde
	s_movk_i32 s8, 0xb00
	v_cmp_eq_u32_e64 s[36:37], 0, v136
	v_lshrrev_b32_e32 v137, 1, v137
	v_mul_lo_u32 v136, v139, s8
	s_mov_b32 s20, 0xb000
	v_or_b32_e32 v147, s0, v147
	v_mad_u64_u32 v[136:137], s[0:1], v137, s20, v[136:137]
	v_or_b32_e32 v136, v136, v138
	v_lshrrev_b32_e32 v139, 1, v141
	v_mul_lo_u32 v138, v143, s8
	v_lshl_or_b32 v149, v146, 6, v149
	v_lshlrev_b32_e32 v146, 2, v146
	v_mad_u64_u32 v[138:139], s[0:1], v139, s20, v[138:139]
	v_and_b32_e32 v146, 32, v146
	s_waitcnt vmcnt(6)
	v_or_b32_e32 v138, v138, v142
	v_bitop3_b32 v146, v149, s22, v146 bitop3:0xde
	v_add_u32_e32 v146, 0x10000, v146
	v_add_lshl_u32 v136, v136, v140, 1
	v_mov_b32_e32 v137, v1
	s_mov_b64 s[22:23], 0xb0080
	v_add_lshl_u32 v138, v138, v148, 1
	v_mov_b32_e32 v139, v1
	v_lshlrev_b32_e32 v126, 16, v62
	v_and_b32_e32 v127, 0xffff0000, v62
	v_lshlrev_b32_e32 v128, 16, v63
	v_and_b32_e32 v129, 0xffff0000, v63
	v_lshlrev_b32_e32 v122, 16, v64
	v_and_b32_e32 v123, 0xffff0000, v64
	v_lshlrev_b32_e32 v124, 16, v65
	v_and_b32_e32 v125, 0xffff0000, v65
	v_lshlrev_b32_e32 v110, 16, v58
	v_and_b32_e32 v111, 0xffff0000, v58
	v_lshlrev_b32_e32 v112, 16, v59
	v_and_b32_e32 v113, 0xffff0000, v59
	v_lshlrev_b32_e32 v106, 16, v60
	v_and_b32_e32 v107, 0xffff0000, v60
	v_lshlrev_b32_e32 v108, 16, v61
	v_and_b32_e32 v109, 0xffff0000, v61
	v_lshlrev_b32_e32 v102, 16, v46
	v_and_b32_e32 v103, 0xffff0000, v46
	v_lshlrev_b32_e32 v104, 16, v47
	v_and_b32_e32 v105, 0xffff0000, v47
	v_lshlrev_b32_e32 v98, 16, v48
	v_and_b32_e32 v99, 0xffff0000, v48
	v_lshlrev_b32_e32 v100, 16, v49
	v_and_b32_e32 v101, 0xffff0000, v49
	v_lshlrev_b32_e32 v86, 16, v38
	v_and_b32_e32 v87, 0xffff0000, v38
	v_lshlrev_b32_e32 v88, 16, v39
	v_and_b32_e32 v89, 0xffff0000, v39
	v_lshlrev_b32_e32 v82, 16, v40
	v_and_b32_e32 v83, 0xffff0000, v40
	v_lshlrev_b32_e32 v84, 16, v41
	v_and_b32_e32 v85, 0xffff0000, v41
	v_lshlrev_b32_e32 v78, 16, v42
	v_and_b32_e32 v79, 0xffff0000, v42
	v_lshlrev_b32_e32 v80, 16, v43
	v_and_b32_e32 v81, 0xffff0000, v43
	v_lshlrev_b32_e32 v74, 16, v44
	v_and_b32_e32 v75, 0xffff0000, v44
	v_lshlrev_b32_e32 v76, 16, v45
	v_and_b32_e32 v77, 0xffff0000, v45
	v_lshlrev_b32_e32 v62, 16, v34
	v_and_b32_e32 v63, 0xffff0000, v34
	v_lshlrev_b32_e32 v64, 16, v35
	v_and_b32_e32 v65, 0xffff0000, v35
	v_lshlrev_b32_e32 v58, 16, v36
	v_and_b32_e32 v59, 0xffff0000, v36
	v_lshlrev_b32_e32 v60, 16, v37
	v_and_b32_e32 v61, 0xffff0000, v37
	v_lshlrev_b32_e32 v46, 16, v22
	v_and_b32_e32 v47, 0xffff0000, v22
	v_lshlrev_b32_e32 v48, 16, v23
	v_and_b32_e32 v49, 0xffff0000, v23
	v_lshlrev_b32_e32 v42, 16, v24
	v_and_b32_e32 v43, 0xffff0000, v24
	v_lshlrev_b32_e32 v44, 16, v25
	v_and_b32_e32 v45, 0xffff0000, v25
	v_lshlrev_b32_e32 v38, 16, v14
	v_and_b32_e32 v39, 0xffff0000, v14
	v_lshlrev_b32_e32 v40, 16, v15
	v_and_b32_e32 v41, 0xffff0000, v15
	v_lshlrev_b32_e32 v34, 16, v16
	v_and_b32_e32 v35, 0xffff0000, v16
	v_lshlrev_b32_e32 v36, 16, v17
	v_and_b32_e32 v37, 0xffff0000, v17
	v_lshlrev_b32_e32 v30, 16, v18
	v_and_b32_e32 v31, 0xffff0000, v18
	v_lshlrev_b32_e32 v32, 16, v19
	v_and_b32_e32 v33, 0xffff0000, v19
	v_lshlrev_b32_e32 v26, 16, v20
	v_and_b32_e32 v27, 0xffff0000, v20
	v_lshlrev_b32_e32 v28, 16, v21
	v_and_b32_e32 v29, 0xffff0000, v21
	v_lshlrev_b32_e32 v22, 16, v6
	v_and_b32_e32 v23, 0xffff0000, v6
	v_lshlrev_b32_e32 v24, 16, v7
	v_and_b32_e32 v25, 0xffff0000, v7
	v_lshlrev_b32_e32 v18, 16, v8
	v_and_b32_e32 v19, 0xffff0000, v8
	v_lshlrev_b32_e32 v20, 16, v9
	v_and_b32_e32 v21, 0xffff0000, v9
	v_lshlrev_b32_e32 v14, 16, v10
	v_and_b32_e32 v15, 0xffff0000, v10
	v_lshlrev_b32_e32 v16, 16, v11
	v_and_b32_e32 v17, 0xffff0000, v11
	v_lshlrev_b32_e32 v10, 16, v12
	v_and_b32_e32 v11, 0xffff0000, v12
	v_lshlrev_b32_e32 v12, 16, v13
	v_and_b32_e32 v13, 0xffff0000, v13
	v_lshlrev_b32_e32 v6, 16, v2
	v_and_b32_e32 v7, 0xffff0000, v2
	v_lshlrev_b32_e32 v8, 16, v3
	v_and_b32_e32 v9, 0xffff0000, v3
	v_lshlrev_b32_e32 v2, 16, v4
	v_and_b32_e32 v3, 0xffff0000, v4
	v_lshlrev_b32_e32 v4, 16, v5
	v_and_b32_e32 v5, 0xffff0000, v5
	s_mov_b32 s42, 0
	v_lshl_add_u64 v[136:137], v[136:137], 0, s[22:23]
	v_lshl_add_u64 v[138:139], v[138:139], 0, s[22:23]
	s_barrier
	s_branch .LBB0_673
